# MLA attention tile loop rewritten by hand: QK of key-half 1 issued under exp of half 0 (2-stage software pipeline), bf16 MFMA f32 acc unchanged
# speedup vs baseline: 1.0129x; 1.0129x over previous
; #define ATT_ISSUE(kt) do { kreg0 = *(const u32x4*)(Kg + (size_t)((kt) * 64 + kr0) * ldk + kc0 * 8); \
;         if (has1) kreg1 = *(const u32x4*)(Kg + (size_t)((kt) * 64 + kr1) * ldk + kc1 * 8); \
;         vreg = *(const u32x4*)(Vtg + (size_t)ve * TB + (kt) * 64 + vc * 8); } while (0)
; template <int DQK, bool MASK, int NQ>
; __device__ __forceinline__ void attn_unit(unsigned char* lds, const bf16_t* Qg, int ldq, const bf16_t* Kg, int ldk, const bf16_t* Vtg, bf16_t* Og, int ldo,
;                                           int qi0, int a0, int n1, int b0, int n2, float m0, bool sink) {
;     ...
;     f32x4 o[4][NQ];
; #pragma unroll
;     for (int eb = 0; eb < 4; ++eb)
; #pragma unroll
;         for (int qb = 0; qb < NQ; ++qb) o[eb][qb] = (f32x4){0.f, 0.f, 0.f, 0.f};
;     float mrow[NQ]; f32x4 negm[NQ], ol[NQ];
; #pragma unroll
;     for (int qb = 0; qb < NQ; ++qb) { mrow[qb] = sink ? m0 : 0.f; const float l0 = sink ? 1.f : 0.f; ol[qb] = (f32x4){l0, l0, l0, l0}; negm[qb] = (f32x4){-mrow[qb], -mrow[qb], -mrow[qb], -mrow[qb]}; }
;     const bf16x8 ones = (bf16x8){0x3F80, 0x3F80, 0x3F80, 0x3F80, 0x3F80, 0x3F80, 0x3F80, 0x3F80};
;     bool first = !sink;
;     int nt = n1 + n2; asm volatile("" : "+s"(nt));
;     const int kr0 = tid & 63, kc0 = tid >> 6;
;     const int ci1 = tid + 512, kr1 = ci1 & 63, kc1 = ci1 >> 6;
;     const bool has1 = (KCH * 64 > 512) && (ci1 < KCH * 64);
;     const int ve = tid >> 3, vc = tid & 7;
;     const int mA_ = 2 * vc, mB_ = 2 * vc + 1;
;     const int voffA = ((mA_ >> 3) * 4 + (mA_ & 3)) * 16 + ((mA_ & 7) >> 2) * 8, voffB = ((mB_ >> 3) * 4 + (mB_ & 3)) * 16 + ((mB_ & 7) >> 2) * 8;
;     u32x4 kreg0, kreg1 = (u32x4){0u, 0u, 0u, 0u}, vreg;
;     ...
;     { const int kt0 = ATT_TILE(0); ATT_ISSUE(kt0); ATT_COMMIT(0); }
;     __syncthreads();
; #pragma unroll 1
;     for (int tt = 0; tt < nt; ++tt) {
;         const int kt = ATT_TILE(tt);
;         if (tt + 1 < nt) { const int ktn = ATT_TILE(tt + 1); ATT_ISSUE(ktn); }
.LBB0_478:
	s_or_b64 exec, exec, s[0:1]
	s_lshl_b32 s0, s69, 6
	s_and_b32 s0, s0, 0x3c0
	s_mulk_i32 s0, 0x4200
	s_add_u32 s0, s65, s0
	s_addc_u32 s1, s66, 0
	v_ashrrev_i32_e32 v2, 3, v5
	v_and_b32_e32 v3, 7, v5
	v_mov_b64_e32 v[8:9], s[0:1]
	s_movk_i32 s0, 0x4200
	v_mad_i64_i32 v[8:9], s[0:1], v2, s0, v[8:9]
	v_lshlrev_b32_e32 v10, 4, v3
	v_mov_b32_e32 v11, v36
	v_lshl_add_u64 v[214:215], v[8:9], 0, v[10:11]
	global_load_dwordx4 v[148:151], v[214:215], off
	v_lshlrev_b32_e32 v201, 10, v1
	v_lshlrev_b32_e32 v205, 4, v43
	v_add3_u32 v1, 0, v201, v205
	v_lshlrev_b32_e32 v207, 10, v6
	s_waitcnt vmcnt(0)
	ds_write_b128 v1, v[140:143]
	s_and_saveexec_b64 s[0:1], s[38:39]
	v_add3_u32 v1, 0, v207, v205
	ds_write_b128 v1, v[144:147]
	s_or_b64 exec, exec, s[0:1]
	v_lshlrev_b32_e32 v1, 1, v3
	v_and_b32_e32 v3, 4, v5
	v_and_or_b32 v1, v1, 2, v3
	v_lshlrev_b32_e32 v3, 2, v5
	v_and_b32_e32 v3, 8, v3
	v_lshl_or_b32 v1, v1, 4, v3
	v_mul_lo_u32 v2, v2, s76
	v_add3_u32 v209, 0, v2, v1
	v_bfe_u32 v41, v5, 4, 2
	v_add_u32_e32 v1, 0x6000, v209
	s_cmp_lt_i32 s19, 1
	ds_write2_b64 v1, v[148:149], v[150:151] offset1:2
	s_waitcnt lgkmcnt(0)
	s_barrier
	s_cbranch_scc1 .LBB0_404
	v_add_u32_e32 v205, v201, v205
	v_add_u32_e32 v37, 0xd000, v205
	ds_write_b128 v37, v[44:47]
	ds_write_b128 v37, v[200:203] offset:8192
	ds_write_b128 v37, v[216:219] offset:16384
	ds_write_b128 v37, v[220:223] offset:24576
	ds_write_b128 v37, v[224:227] offset:32768
	ds_write_b128 v37, v[228:231] offset:40960
	ds_write_b128 v37, v[232:235] offset:49152
	ds_write_b32 v37, v40 offset:57344
	ds_write_b64 v37, v[250:251] offset:57352
	v_lshlrev_b32_e32 v1, 10, v41
	v_lshlrev_b32_e32 v2, 4, v4
	v_mul_u32_u24_e32 v3, 0x90, v4
	s_waitcnt lgkmcnt(0)
	v_add3_u32 v250, 0, v1, v2
	v_add3_u32 v251, 0, v0, v3
	v_mov_b32_e32 v37, v36
	v_mov_b32_e32 v38, v36
	v_mov_b32_e32 v39, v36
	v_mov_b64_e32 v[0:1], v[36:37]
	v_mov_b64_e32 v[2:3], v[36:37]
	v_mov_b64_e32 v[4:5], v[36:37]
	v_mov_b64_e32 v[6:7], v[36:37]
	v_mov_b64_e32 v[8:9], v[36:37]
	v_mov_b64_e32 v[10:11], v[36:37]
	v_mov_b64_e32 v[12:13], v[36:37]
	v_mov_b64_e32 v[14:15], v[36:37]
	v_mov_b64_e32 v[16:17], v[36:37]
	v_mov_b64_e32 v[18:19], v[36:37]
	v_mov_b64_e32 v[20:21], v[36:37]
	v_mov_b64_e32 v[22:23], v[36:37]
	v_mov_b64_e32 v[24:25], v[36:37]
	v_mov_b64_e32 v[26:27], v[36:37]
	v_mov_b64_e32 v[28:29], v[36:37]
	v_mov_b64_e32 v[30:31], v[36:37]
	v_mov_b64_e32 v[32:33], v[36:37]
	v_mov_b64_e32 v[34:35], v[36:37]
	v_mov_b64_e32 v[48:49], v[36:37]
	v_mov_b64_e32 v[50:51], v[36:37]
	v_mov_b64_e32 v[52:53], v[36:37]
	v_mov_b64_e32 v[54:55], v[36:37]
	v_mov_b64_e32 v[56:57], v[36:37]
	v_mov_b64_e32 v[58:59], v[36:37]
	v_mov_b64_e32 v[60:61], v[36:37]
	v_mov_b64_e32 v[62:63], v[36:37]
	v_mov_b64_e32 v[64:65], v[36:37]
	v_mov_b64_e32 v[66:67], v[36:37]
	v_mov_b64_e32 v[68:69], v[36:37]
	v_mov_b64_e32 v[70:71], v[36:37]
	v_mov_b64_e32 v[72:73], v[36:37]
	v_mov_b64_e32 v[74:75], v[36:37]
	v_mov_b64_e32 v[76:77], v[36:37]
	v_mov_b64_e32 v[78:79], v[36:37]
	v_mov_b64_e32 v[80:81], v[36:37]
	v_mov_b64_e32 v[82:83], v[36:37]
	v_mov_b64_e32 v[84:85], v[36:37]
	v_mov_b64_e32 v[86:87], v[36:37]
	v_mov_b64_e32 v[88:89], v[36:37]
	v_mov_b64_e32 v[90:91], v[36:37]
	v_mov_b32_e32 v241, 0
	v_mov_b32_e32 v240, 0
	v_mov_b32_e32 v255, 0
	v_mov_b32_e32 v40, 0
	v_bfrev_b32_e32 v152, 1
	v_mov_b32_e32 v153, v152
	v_mov_b32_e32 v154, v152
	v_mov_b32_e32 v155, v152
	v_mov_b32_e32 v156, v152
	v_mov_b32_e32 v157, v152
	v_mov_b32_e32 v158, v152
	v_mov_b32_e32 v159, v152
	v_mov_b32_e32 v160, v152
	v_mov_b32_e32 v161, v152
	v_mov_b32_e32 v162, v152
	v_mov_b32_e32 v163, v152
	v_mov_b32_e32 v164, v152
	v_mov_b32_e32 v165, v152
	v_mov_b32_e32 v166, v152
	v_mov_b32_e32 v167, v152
	s_mov_b32 s13, 0
	s_mov_b64 s[10:11], -1
.Lmla_tile:
	s_add_i32 s24, s13, 1
	s_cmp_ge_i32 s24, s19
	s_cbranch_scc1 .Lmla_noload
	v_mov_b32_e32 v37, s24
	v_lshlrev_b32_e32 v38, 6, v37
	v_or_b32_e32 v37, v38, v43
	s_movk_i32 s0, 0x600
	v_mov_b64_e32 v[140:141], s[2:3]
	s_nop 0
	v_mad_i64_i32 v[148:149], s[0:1], v37, s0, v[140:141]
	v_lshl_add_u64 v[140:141], v[210:211], 1, v[148:149]
	global_load_dwordx4 v[140:143], v[140:141], off
	s_and_saveexec_b64 s[0:1], s[38:39]
	s_cbranch_execz .Lmla_nok1
	v_lshl_add_u64 v[144:145], v[212:213], 1, v[148:149]
	global_load_dwordx4 v[144:147], v[144:145], off

; template <int DQK, bool MASK, int NQ>
; __device__ __forceinline__ void attn_unit(unsigned char* lds, const bf16_t* Qg, int ldq, const bf16_t* Kg, int ldk, const bf16_t* Vtg, bf16_t* Og, int ldo,
;                                           int qi0, int a0, int n1, int b0, int n2, float m0, bool sink) {
;     ...
;             { const unsigned char* kb_ = lds + KOFF + (tt & 1) * KBYTES + hb * 512 + g * 1024 + ql * 16;
;               __builtin_amdgcn_s_setprio(1);
; #pragma unroll
;               for (int k2 = 0; k2 < 2; ++k2) {
; #pragma unroll
;                   for (int c = 0; c < NC; ++c) {
;                       const bf16x8 kf = *(const bf16x8*)(kb_ + c * 4096 + k2 * 256);
; #pragma unroll
;                       for (int qb = 0; qb < NQ; ++qb) sc[k2][qb] = __builtin_amdgcn_mfma_f32_16x16x32_bf16(kf, qf[qb][c], c == 0 ? negm[qb] : sc[k2][qb], 0, 0, 0);
;                   } }
;               __builtin_amdgcn_s_setprio(0); }
;             if (MASK) { if (kt >= 4) { int dl = kt * 64 + hb * 32 + g * 4 - qw0 - ql; asm volatile("" : "+v"(dl));
; #pragma unroll
;                 for (int k2 = 0; k2 < 2; ++k2)
; #pragma unroll
;                     for (int qb = 0; qb < NQ; ++qb)
; #pragma unroll
;                         for (int j = 0; j < 4; ++j) { const int d = dl + (k2 * 16 + j - qb * 16); if (d > 128 || d < -128) sc[k2][qb][j] = -1e30f; } } }
;             float am = fmaxf(fmaxf(sc[0][0][0], sc[0][0][1]), sc[0][0][2]); am = fmaxf(fmaxf(am, sc[0][0][3]), sc[1][0][0]); am = fmaxf(fmaxf(am, sc[1][0][1]), sc[1][0][2]); am = fmaxf(am, sc[1][0][3]);
; #pragma unroll
;             for (int qb = 1; qb < NQ; ++qb) { am = fmaxf(fmaxf(am, sc[0][qb][0]), sc[0][qb][1]); am = fmaxf(fmaxf(am, sc[0][qb][2]), sc[0][qb][3]);
;                 am = fmaxf(fmaxf(am, sc[1][qb][0]), sc[1][qb][1]); am = fmaxf(fmaxf(am, sc[1][qb][2]), sc[1][qb][3]); }
;             if (__any(first || (am > ATT_THR))) {
; #pragma unroll
;                 for (int qb = 0; qb < NQ; ++qb) {
;                     float a = fmaxf(fmaxf(sc[0][qb][0], sc[0][qb][1]), sc[0][qb][2]);
;                     a = fmaxf(fmaxf(a, sc[0][qb][3]), sc[1][qb][0]); a = fmaxf(fmaxf(a, sc[1][qb][1]), sc[1][qb][2]); a = fmaxf(a, sc[1][qb][3]);
;                     { auto r16 = __builtin_amdgcn_permlane16_swap(__float_as_uint(a), __float_as_uint(a), false, false); a = fmaxf(__uint_as_float(r16[0]), __uint_as_float(r16[1])); }
.Lmla_noload:
	s_and_b32 s0, s13, 1
	s_mul_i32 s1, s0, 0x3000
	s_mulk_i32 s0, 0x2400
	v_add_u32_e32 v37, s1, v250
	v_add_u32_e32 v38, s0, v251
	ds_read_b128 v[196:199], v37
	ds_read_b128 v[192:195], v37 offset:4096
	ds_read_b128 v[188:191], v37 offset:8192
	ds_read_b128 v[184:187], v37 offset:256
	ds_read_b128 v[242:245], v37 offset:4352
	ds_read_b128 v[246:249], v37 offset:8448
	s_waitcnt lgkmcnt(5)
	v_mfma_f32_16x16x32_bf16 v[180:183], v[196:199], v[92:95], v[160:163]
	v_mfma_f32_16x16x32_bf16 v[176:179], v[196:199], v[104:107], v[156:159]
	v_mfma_f32_16x16x32_bf16 v[172:175], v[196:199], v[116:119], v[152:155]
	v_mfma_f32_16x16x32_bf16 v[168:171], v[196:199], v[128:131], v[164:167]
	s_waitcnt lgkmcnt(4)
	v_mfma_f32_16x16x32_bf16 v[180:183], v[192:195], v[96:99], v[180:183]
	v_mfma_f32_16x16x32_bf16 v[176:179], v[192:195], v[108:111], v[176:179]
	v_mfma_f32_16x16x32_bf16 v[172:175], v[192:195], v[120:123], v[172:175]
	v_mfma_f32_16x16x32_bf16 v[168:171], v[192:195], v[132:135], v[168:171]
	s_waitcnt lgkmcnt(3)
	v_mfma_f32_16x16x32_bf16 v[180:183], v[188:191], v[100:103], v[180:183]
	v_mfma_f32_16x16x32_bf16 v[176:179], v[188:191], v[112:115], v[176:179]
	v_mfma_f32_16x16x32_bf16 v[172:175], v[188:191], v[124:127], v[172:175]
	v_mfma_f32_16x16x32_bf16 v[168:171], v[188:191], v[136:139], v[168:171]
	s_waitcnt lgkmcnt(2)
	v_mfma_f32_16x16x32_bf16 v[196:199], v[184:187], v[92:95], v[160:163]
	v_mfma_f32_16x16x32_bf16 v[192:195], v[184:187], v[104:107], v[156:159]
	v_mfma_f32_16x16x32_bf16 v[188:191], v[184:187], v[116:119], v[152:155]
	v_mfma_f32_16x16x32_bf16 v[184:187], v[184:187], v[128:131], v[164:167]
	s_waitcnt lgkmcnt(1)
	v_mfma_f32_16x16x32_bf16 v[196:199], v[242:245], v[96:99], v[196:199]
	v_mfma_f32_16x16x32_bf16 v[192:195], v[242:245], v[108:111], v[192:195]
	v_mfma_f32_16x16x32_bf16 v[188:191], v[242:245], v[120:123], v[188:191]
	v_mfma_f32_16x16x32_bf16 v[184:187], v[242:245], v[132:135], v[184:187]
	s_waitcnt lgkmcnt(0)
	v_mfma_f32_16x16x32_bf16 v[196:199], v[246:249], v[100:103], v[196:199]
	v_mfma_f32_16x16x32_bf16 v[192:195], v[246:249], v[112:115], v[192:195]
	v_mfma_f32_16x16x32_bf16 v[188:191], v[246:249], v[124:127], v[188:191]
	v_mfma_f32_16x16x32_bf16 v[184:187], v[246:249], v[136:139], v[184:187]
	v_max_f32_e32 v216, v180, v181
	v_max_f32_e32 v217, v176, v177
	v_max_f32_e32 v218, v172, v173
	v_max_f32_e32 v219, v168, v169
	v_max3_f32 v216, v216, v182, v183
	v_max3_f32 v217, v217, v178, v179
	v_max3_f32 v218, v218, v174, v175
	v_max3_f32 v219, v219, v170, v171
	v_max3_f32 v216, v216, v196, v197
	v_max3_f32 v217, v217, v192, v193
	v_max3_f32 v218, v218, v188, v189
	v_max3_f32 v219, v219, v184, v185
	v_max3_f32 v216, v216, v198, v199
	v_max3_f32 v217, v217, v194, v195
	v_max3_f32 v218, v218, v190, v191
	v_max3_f32 v219, v219, v186, v187
	v_max3_f32 v220, v216, v217, v218
	v_max_f32_e32 v220, v220, v219
	v_cmp_lt_f32_e32 vcc, 4.0, v220
	s_or_b64 s[0:1], s[10:11], vcc
	s_cmp_lg_u64 s[0:1], 0
	s_cbranch_scc1 .Lmla_rare_a
.Lmla_common_a:
	ds_read_b128 v[232:235], v37 offset:512
	ds_read_b128 v[44:47], v37 offset:4608
	ds_read_b128 v[200:203], v37 offset:8704
	ds_read_b128 v[236:239], v37 offset:768
	ds_read_b128 v[242:245], v37 offset:4864
	ds_read_b128 v[246:249], v37 offset:8960
	s_waitcnt lgkmcnt(5)
	v_mfma_f32_16x16x32_bf16 v[216:219], v[232:235], v[92:95], v[160:163]
	v_exp_f32_e32 v180, v180
	v_exp_f32_e32 v181, v181
	v_mfma_f32_16x16x32_bf16 v[220:223], v[232:235], v[104:107], v[156:159]
	v_exp_f32_e32 v182, v182
	v_exp_f32_e32 v183, v183
	v_mfma_f32_16x16x32_bf16 v[224:227], v[232:235], v[116:119], v[152:155]
	v_exp_f32_e32 v196, v196
	v_exp_f32_e32 v197, v197
	v_mfma_f32_16x16x32_bf16 v[228:231], v[232:235], v[128:131], v[164:167]
	v_exp_f32_e32 v198, v198
	v_exp_f32_e32 v199, v199
	s_waitcnt lgkmcnt(4)
	v_mfma_f32_16x16x32_bf16 v[216:219], v[44:47], v[96:99], v[216:219]
	v_cvt_pk_bf16_f32 v180, v180, v181
	v_cvt_pk_bf16_f32 v181, v182, v183
	v_mfma_f32_16x16x32_bf16 v[220:223], v[44:47], v[108:111], v[220:223]
	v_cvt_pk_bf16_f32 v182, v196, v197
	v_cvt_pk_bf16_f32 v183, v198, v199
	v_mfma_f32_16x16x32_bf16 v[224:227], v[44:47], v[120:123], v[224:227]
	v_exp_f32_e32 v176, v176
	v_exp_f32_e32 v177, v177
	v_mfma_f32_16x16x32_bf16 v[228:231], v[44:47], v[132:135], v[228:231]
	v_exp_f32_e32 v178, v178
	v_exp_f32_e32 v179, v179
	s_waitcnt lgkmcnt(3)
	v_mfma_f32_16x16x32_bf16 v[216:219], v[200:203], v[100:103], v[216:219]
	v_exp_f32_e32 v192, v192
	v_exp_f32_e32 v193, v193
	v_mfma_f32_16x16x32_bf16 v[220:223], v[200:203], v[112:115], v[220:223]
	v_exp_f32_e32 v194, v194
	v_exp_f32_e32 v195, v195
	v_mfma_f32_16x16x32_bf16 v[224:227], v[200:203], v[124:127], v[224:227]
	v_cvt_pk_bf16_f32 v176, v176, v177
	v_cvt_pk_bf16_f32 v177, v178, v179
	v_mfma_f32_16x16x32_bf16 v[228:231], v[200:203], v[136:139], v[228:231]
	v_cvt_pk_bf16_f32 v178, v192, v193
	v_cvt_pk_bf16_f32 v179, v194, v195
	s_waitcnt lgkmcnt(2)
	v_mfma_f32_16x16x32_bf16 v[232:235], v[236:239], v[92:95], v[160:163]
	v_exp_f32_e32 v172, v172
	v_exp_f32_e32 v173, v173
	v_mfma_f32_16x16x32_bf16 v[44:47], v[236:239], v[104:107], v[156:159]
	v_exp_f32_e32 v174, v174
	v_exp_f32_e32 v175, v175
	v_mfma_f32_16x16x32_bf16 v[200:203], v[236:239], v[116:119], v[152:155]
	v_exp_f32_e32 v188, v188
	v_exp_f32_e32 v189, v189
	v_mfma_f32_16x16x32_bf16 v[236:239], v[236:239], v[128:131], v[164:167]
	v_exp_f32_e32 v190, v190
	v_exp_f32_e32 v191, v191
	s_waitcnt lgkmcnt(1)
; template <int DQK, bool MASK, int NQ>
; __device__ __forceinline__ void attn_unit(unsigned char* lds, const bf16_t* Qg, int ldq, const bf16_t* Kg, int ldk, const bf16_t* Vtg, bf16_t* Og, int ldo,
;                                           int qi0, int a0, int n1, int b0, int n2, float m0, bool sink) {
;     ...
;             float am = fmaxf(fmaxf(sc[0][0][0], sc[0][0][1]), sc[0][0][2]); am = fmaxf(fmaxf(am, sc[0][0][3]), sc[1][0][0]); am = fmaxf(fmaxf(am, sc[1][0][1]), sc[1][0][2]); am = fmaxf(am, sc[1][0][3]);
; #pragma unroll
;             for (int qb = 1; qb < NQ; ++qb) { am = fmaxf(fmaxf(am, sc[0][qb][0]), sc[0][qb][1]); am = fmaxf(fmaxf(am, sc[0][qb][2]), sc[0][qb][3]);
;                 am = fmaxf(fmaxf(am, sc[1][qb][0]), sc[1][qb][1]); am = fmaxf(fmaxf(am, sc[1][qb][2]), sc[1][qb][3]); }
;             if (__any(first || (am > ATT_THR))) {
; #pragma unroll
;                 for (int qb = 0; qb < NQ; ++qb) {
;                     float a = fmaxf(fmaxf(sc[0][qb][0], sc[0][qb][1]), sc[0][qb][2]);
;                     a = fmaxf(fmaxf(a, sc[0][qb][3]), sc[1][qb][0]); a = fmaxf(fmaxf(a, sc[1][qb][1]), sc[1][qb][2]); a = fmaxf(a, sc[1][qb][3]);
;                     { auto r16 = __builtin_amdgcn_permlane16_swap(__float_as_uint(a), __float_as_uint(a), false, false); a = fmaxf(__uint_as_float(r16[0]), __uint_as_float(r16[1])); }
;                     { auto r32 = __builtin_amdgcn_permlane32_swap(__float_as_uint(a), __float_as_uint(a), false, false); a = fmaxf(__uint_as_float(r32[0]), __uint_as_float(r32[1])); }
;                     const float dlt = first ? a : fmaxf(a, 0.f);
;                     mrow[qb] += dlt; negm[qb] = (f32x4){-mrow[qb], -mrow[qb], -mrow[qb], -mrow[qb]};
;                     sc[0][qb] = sc[0][qb] - dlt; sc[1][qb] = sc[1][qb] - dlt;
;                     if (!first) { const float alpha = __builtin_amdgcn_exp2f(-dlt); ol[qb] = ol[qb] * alpha;
; #pragma unroll
;                         for (int eb = 0; eb < 4; ++eb) o[eb][qb] = o[eb][qb] * alpha; } }
;                 first = false; }
;             bf16x8 pf[NQ];
; #pragma unroll
;             for (int qb = 0; qb < NQ; ++qb) {
; #pragma unroll
;                 for (int k2 = 0; k2 < 2; ++k2)
; #pragma unroll
;                     for (int j = 0; j < 4; ++j) sc[k2][qb][j] = __builtin_amdgcn_exp2f(sc[k2][qb][j]);
	v_mfma_f32_16x16x32_bf16 v[232:235], v[242:245], v[96:99], v[232:235]
	v_cvt_pk_bf16_f32 v172, v172, v173
	v_cvt_pk_bf16_f32 v173, v174, v175
	v_mfma_f32_16x16x32_bf16 v[44:47], v[242:245], v[108:111], v[44:47]
	v_cvt_pk_bf16_f32 v174, v188, v189
	v_cvt_pk_bf16_f32 v175, v190, v191
	v_mfma_f32_16x16x32_bf16 v[200:203], v[242:245], v[120:123], v[200:203]
	v_exp_f32_e32 v168, v168
	v_exp_f32_e32 v169, v169
	v_mfma_f32_16x16x32_bf16 v[236:239], v[242:245], v[132:135], v[236:239]
	v_exp_f32_e32 v170, v170
	v_exp_f32_e32 v171, v171
	s_waitcnt lgkmcnt(0)
	v_mfma_f32_16x16x32_bf16 v[232:235], v[246:249], v[100:103], v[232:235]
	v_exp_f32_e32 v184, v184
	v_exp_f32_e32 v185, v185
	v_mfma_f32_16x16x32_bf16 v[44:47], v[246:249], v[112:115], v[44:47]
	v_exp_f32_e32 v186, v186
	v_exp_f32_e32 v187, v187
	v_mfma_f32_16x16x32_bf16 v[200:203], v[246:249], v[124:127], v[200:203]
	v_cvt_pk_bf16_f32 v168, v168, v169
	v_cvt_pk_bf16_f32 v169, v170, v171
	v_mfma_f32_16x16x32_bf16 v[236:239], v[246:249], v[136:139], v[236:239]
	v_cvt_pk_bf16_f32 v170, v184, v185
	v_cvt_pk_bf16_f32 v171, v186, v187
	ds_read_b128 v[196:199], v38 offset:24576
	ds_read_b128 v[192:195], v38 offset:26880
	ds_read_b128 v[188:191], v38 offset:29184
	ds_read_b128 v[184:187], v38 offset:31488
	v_mov_b32_e32 v246, s12
	v_mov_b32_e32 v247, s12
	v_mov_b32_e32 v248, s12
	v_mov_b32_e32 v249, s12
	v_max_f32_e32 v242, v216, v217
	v_max_f32_e32 v243, v220, v221
	v_max_f32_e32 v244, v224, v225
	v_max_f32_e32 v245, v228, v229
	v_max3_f32 v242, v242, v218, v219
	v_max3_f32 v243, v243, v222, v223
	v_max3_f32 v244, v244, v226, v227
	v_max3_f32 v245, v245, v230, v231
	v_max3_f32 v242, v242, v232, v233
	v_max3_f32 v243, v243, v44, v45
	v_max3_f32 v244, v244, v200, v201
	v_max3_f32 v245, v245, v236, v237
	v_max3_f32 v242, v242, v234, v235
	v_max3_f32 v243, v243, v46, v47
	v_max3_f32 v244, v244, v202, v203
	v_max3_f32 v245, v245, v238, v239
	v_max3_f32 v39, v242, v243, v244
	v_max_f32_e32 v39, v39, v245
	s_waitcnt lgkmcnt(3)
	v_mfma_f32_16x16x32_bf16 v[76:79], v[196:199], v[180:183], v[76:79]
	v_mfma_f32_16x16x32_bf16 v[56:59], v[196:199], v[176:179], v[56:59]
	v_mfma_f32_16x16x32_bf16 v[24:27], v[196:199], v[172:175], v[24:27]
	v_mfma_f32_16x16x32_bf16 v[4:7], v[196:199], v[168:171], v[4:7]
	s_waitcnt lgkmcnt(2)
	v_mfma_f32_16x16x32_bf16 v[80:83], v[192:195], v[180:183], v[80:83]
	v_mfma_f32_16x16x32_bf16 v[60:63], v[192:195], v[176:179], v[60:63]
	v_mfma_f32_16x16x32_bf16 v[28:31], v[192:195], v[172:175], v[28:31]
	v_mfma_f32_16x16x32_bf16 v[8:11], v[192:195], v[168:171], v[8:11]
	s_waitcnt lgkmcnt(1)
	v_mfma_f32_16x16x32_bf16 v[84:87], v[188:191], v[180:183], v[84:87]
	v_mfma_f32_16x16x32_bf16 v[64:67], v[188:191], v[176:179], v[64:67]
	v_mfma_f32_16x16x32_bf16 v[32:35], v[188:191], v[172:175], v[32:35]
	v_mfma_f32_16x16x32_bf16 v[12:15], v[188:191], v[168:171], v[12:15]
	s_waitcnt lgkmcnt(0)
	v_mfma_f32_16x16x32_bf16 v[72:75], v[184:187], v[180:183], v[72:75]
	v_mfma_f32_16x16x32_bf16 v[52:55], v[184:187], v[176:179], v[52:55]
	v_mfma_f32_16x16x32_bf16 v[20:23], v[184:187], v[172:175], v[20:23]
	v_mfma_f32_16x16x32_bf16 v[0:3], v[184:187], v[168:171], v[0:3]
	v_mfma_f32_16x16x32_bf16 v[88:91], v[246:249], v[180:183], v[88:91]
	v_mfma_f32_16x16x32_bf16 v[68:71], v[246:249], v[176:179], v[68:71]
	v_mfma_f32_16x16x32_bf16 v[48:51], v[246:249], v[172:175], v[48:51]
	v_mfma_f32_16x16x32_bf16 v[16:19], v[246:249], v[168:171], v[16:19]
	v_cmp_lt_f32_e32 vcc, 4.0, v39
	s_or_b64 s[0:1], s[10:11], vcc
	s_cmp_lg_u64 s[0:1], 0
	s_cbranch_scc1 .Lmla_rare_b
.Lmla_common_b:
	ds_read_b128 v[196:199], v38 offset:24640
	ds_read_b128 v[192:195], v38 offset:26944
	ds_read_b128 v[188:191], v38 offset:29248
	ds_read_b128 v[184:187], v38 offset:31552
	v_exp_f32_e32 v216, v216
	v_exp_f32_e32 v217, v217
	v_exp_f32_e32 v218, v218
	v_exp_f32_e32 v219, v219
	v_exp_f32_e32 v232, v232
	v_exp_f32_e32 v233, v233
	v_exp_f32_e32 v234, v234
	v_exp_f32_e32 v235, v235
	v_cvt_pk_bf16_f32 v216, v216, v217
	v_cvt_pk_bf16_f32 v217, v218, v219
	v_cvt_pk_bf16_f32 v218, v232, v233
	v_cvt_pk_bf16_f32 v219, v234, v235
	v_exp_f32_e32 v220, v220
	v_exp_f32_e32 v221, v221
	v_exp_f32_e32 v222, v222
	v_exp_f32_e32 v223, v223
	v_exp_f32_e32 v44, v44
	v_exp_f32_e32 v45, v45
	v_exp_f32_e32 v46, v46
	v_exp_f32_e32 v47, v47
	v_cvt_pk_bf16_f32 v220, v220, v221
	v_cvt_pk_bf16_f32 v221, v222, v223
	v_cvt_pk_bf16_f32 v222, v44, v45
	v_cvt_pk_bf16_f32 v223, v46, v47
	v_exp_f32_e32 v224, v224
	v_exp_f32_e32 v225, v225
	v_exp_f32_e32 v226, v226
	v_exp_f32_e32 v227, v227
	v_exp_f32_e32 v200, v200
	v_exp_f32_e32 v201, v201
	v_exp_f32_e32 v202, v202
	v_exp_f32_e32 v203, v203
	v_cvt_pk_bf16_f32 v224, v224, v225
	v_cvt_pk_bf16_f32 v225, v226, v227
	v_cvt_pk_bf16_f32 v226, v200, v201
	v_cvt_pk_bf16_f32 v227, v202, v203
	v_exp_f32_e32 v228, v228
	v_exp_f32_e32 v229, v229
	v_exp_f32_e32 v230, v230
	v_exp_f32_e32 v231, v231
	v_exp_f32_e32 v236, v236
	v_exp_f32_e32 v237, v237
	v_exp_f32_e32 v238, v238
	v_exp_f32_e32 v239, v239
	v_cvt_pk_bf16_f32 v228, v228, v229
	v_cvt_pk_bf16_f32 v229, v230, v231
	v_cvt_pk_bf16_f32 v230, v236, v237
	v_cvt_pk_bf16_f32 v231, v238, v239
	s_waitcnt lgkmcnt(3)
	v_mfma_f32_16x16x32_bf16 v[76:79], v[196:199], v[216:219], v[76:79]
	v_mfma_f32_16x16x32_bf16 v[56:59], v[196:199], v[220:223], v[56:59]
	v_mfma_f32_16x16x32_bf16 v[24:27], v[196:199], v[224:227], v[24:27]
	v_mfma_f32_16x16x32_bf16 v[4:7], v[196:199], v[228:231], v[4:7]
	s_waitcnt lgkmcnt(2)
	v_mfma_f32_16x16x32_bf16 v[80:83], v[192:195], v[216:219], v[80:83]
	v_mfma_f32_16x16x32_bf16 v[60:63], v[192:195], v[220:223], v[60:63]
	v_mfma_f32_16x16x32_bf16 v[28:31], v[192:195], v[224:227], v[28:31]
	v_mfma_f32_16x16x32_bf16 v[8:11], v[192:195], v[228:231], v[8:11]
	s_waitcnt lgkmcnt(1)
	v_mfma_f32_16x16x32_bf16 v[84:87], v[188:191], v[216:219], v[84:87]
	v_mfma_f32_16x16x32_bf16 v[64:67], v[188:191], v[220:223], v[64:67]
	v_mfma_f32_16x16x32_bf16 v[32:35], v[188:191], v[224:227], v[32:35]
	v_mfma_f32_16x16x32_bf16 v[12:15], v[188:191], v[228:231], v[12:15]
	s_waitcnt lgkmcnt(0)
	v_mfma_f32_16x16x32_bf16 v[72:75], v[184:187], v[216:219], v[72:75]
	v_mfma_f32_16x16x32_bf16 v[52:55], v[184:187], v[220:223], v[52:55]
	v_mfma_f32_16x16x32_bf16 v[20:23], v[184:187], v[224:227], v[20:23]
	v_mfma_f32_16x16x32_bf16 v[0:3], v[184:187], v[228:231], v[0:3]
	v_mfma_f32_16x16x32_bf16 v[88:91], v[246:249], v[216:219], v[88:91]
	v_mfma_f32_16x16x32_bf16 v[68:71], v[246:249], v[220:223], v[68:71]
	v_mfma_f32_16x16x32_bf16 v[48:51], v[246:249], v[224:227], v[48:51]
	v_mfma_f32_16x16x32_bf16 v[16:19], v[246:249], v[228:231], v[16:19]
	s_cmp_ge_i32 s24, s19
	s_cbranch_scc1 .Lmla_nocommit
	s_and_b32 s0, s24, 1
	s_mul_i32 s1, s0, 0x3000
	v_add_u32_e32 v37, s1, v205
	s_waitcnt vmcnt(1)
	ds_write_b128 v37, v[140:143]
	s_and_saveexec_b64 s[14:15], s[38:39]
	ds_write_b128 v37, v[144:147] offset:8192
	s_or_b64 exec, exec, s[14:15]
	s_mulk_i32 s0, 0x2400
	v_add_u32_e32 v37, s0, v209
	v_add_u32_e32 v37, 0x6000, v37
	s_waitcnt vmcnt(0)
	ds_write2_b64 v37, v[148:149], v[150:151] offset1:2

; template <int DQK, bool MASK, int NQ>
; __device__ __forceinline__ void attn_unit(unsigned char* lds, const bf16_t* Qg, int ldq, const bf16_t* Kg, int ldk, const bf16_t* Vtg, bf16_t* Og, int ldo,
;                                           int qi0, int a0, int n1, int b0, int n2, float m0, bool sink) {
;     ...
; #pragma unroll
;                 for (int qb = 0; qb < NQ; ++qb) {
;                     float a = fmaxf(fmaxf(sc[0][qb][0], sc[0][qb][1]), sc[0][qb][2]);
;                     a = fmaxf(fmaxf(a, sc[0][qb][3]), sc[1][qb][0]); a = fmaxf(fmaxf(a, sc[1][qb][1]), sc[1][qb][2]); a = fmaxf(a, sc[1][qb][3]);
;                     { auto r16 = __builtin_amdgcn_permlane16_swap(__float_as_uint(a), __float_as_uint(a), false, false); a = fmaxf(__uint_as_float(r16[0]), __uint_as_float(r16[1])); }
;                     { auto r32 = __builtin_amdgcn_permlane32_swap(__float_as_uint(a), __float_as_uint(a), false, false); a = fmaxf(__uint_as_float(r32[0]), __uint_as_float(r32[1])); }
;                     const float dlt = first ? a : fmaxf(a, 0.f);
;                     mrow[qb] += dlt; negm[qb] = (f32x4){-mrow[qb], -mrow[qb], -mrow[qb], -mrow[qb]};
;                     sc[0][qb] = sc[0][qb] - dlt; sc[1][qb] = sc[1][qb] - dlt;
;                     if (!first) { const float alpha = __builtin_amdgcn_exp2f(-dlt); ol[qb] = ol[qb] * alpha;
; #pragma unroll
;                         for (int eb = 0; eb < 4; ++eb) o[eb][qb] = o[eb][qb] * alpha; } }
;                 first = false; }
.Lmla_rare_a:
	v_mov_b32_e32 v39, v216
	s_nop 1
	v_permlane16_swap_b32_e32 v216, v39
	v_max_f32_e32 v39, v39, v39
	v_max_f32_e32 v216, v216, v216
	v_max_f32_e32 v216, v216, v39
	v_mov_b32_e32 v39, v216
	s_nop 1
	v_permlane32_swap_b32_e32 v216, v39
	v_max_f32_e32 v39, v39, v39
	v_max_f32_e32 v216, v216, v216
	v_max_f32_e32 v216, v216, v39
	v_max_f32_e32 v221, 0, v216
	v_mov_b32_e32 v39, v217
	s_nop 1
	v_permlane16_swap_b32_e32 v217, v39
	v_max_f32_e32 v39, v39, v39
	v_max_f32_e32 v217, v217, v217
	v_max_f32_e32 v217, v217, v39
	v_mov_b32_e32 v39, v217
	s_nop 1
	v_permlane32_swap_b32_e32 v217, v39
	v_max_f32_e32 v39, v39, v39
	v_max_f32_e32 v217, v217, v217
	v_max_f32_e32 v217, v217, v39
	v_max_f32_e32 v222, 0, v217
	v_mov_b32_e32 v39, v218
	s_nop 1
	v_permlane16_swap_b32_e32 v218, v39
	v_max_f32_e32 v39, v39, v39
	v_max_f32_e32 v218, v218, v218
	v_max_f32_e32 v218, v218, v39
	v_mov_b32_e32 v39, v218
	s_nop 1
	v_permlane32_swap_b32_e32 v218, v39
	v_max_f32_e32 v39, v39, v39
	v_max_f32_e32 v218, v218, v218
	v_max_f32_e32 v218, v218, v39
	v_max_f32_e32 v223, 0, v218
	v_mov_b32_e32 v39, v219
	s_nop 1
	v_permlane16_swap_b32_e32 v219, v39
	v_max_f32_e32 v39, v39, v39
	v_max_f32_e32 v219, v219, v219
	v_max_f32_e32 v219, v219, v39
	v_mov_b32_e32 v39, v219
	s_nop 1
	v_permlane32_swap_b32_e32 v219, v39
	v_max_f32_e32 v39, v39, v39
	v_max_f32_e32 v219, v219, v219
	v_max_f32_e32 v219, v219, v39
	v_max_f32_e32 v224, 0, v219
	s_cmp_lg_u64 s[10:11], 0
	s_cbranch_scc1 .Lmla_rare_a_ns
	v_exp_f32_e64 v226, -v221
	v_exp_f32_e64 v228, -v222
	v_exp_f32_e64 v230, -v223
	v_exp_f32_e64 v232, -v224
	s_nop 0
	v_pk_mul_f32 v[88:89], v[88:89], v[226:227] op_sel_hi:[1,0]
	v_pk_mul_f32 v[90:91], v[90:91], v[226:227] op_sel_hi:[1,0]
	v_pk_mul_f32 v[76:77], v[76:77], v[226:227] op_sel_hi:[1,0]
	v_pk_mul_f32 v[78:79], v[78:79], v[226:227] op_sel_hi:[1,0]
	v_pk_mul_f32 v[80:81], v[80:81], v[226:227] op_sel_hi:[1,0]
	v_pk_mul_f32 v[82:83], v[82:83], v[226:227] op_sel_hi:[1,0]
	v_pk_mul_f32 v[84:85], v[84:85], v[226:227] op_sel_hi:[1,0]
	v_pk_mul_f32 v[86:87], v[86:87], v[226:227] op_sel_hi:[1,0]
	v_pk_mul_f32 v[72:73], v[72:73], v[226:227] op_sel_hi:[1,0]
	v_pk_mul_f32 v[74:75], v[74:75], v[226:227] op_sel_hi:[1,0]
	v_pk_mul_f32 v[68:69], v[68:69], v[228:229] op_sel_hi:[1,0]
	v_pk_mul_f32 v[70:71], v[70:71], v[228:229] op_sel_hi:[1,0]
	v_pk_mul_f32 v[56:57], v[56:57], v[228:229] op_sel_hi:[1,0]
	v_pk_mul_f32 v[58:59], v[58:59], v[228:229] op_sel_hi:[1,0]
	v_pk_mul_f32 v[60:61], v[60:61], v[228:229] op_sel_hi:[1,0]
	v_pk_mul_f32 v[62:63], v[62:63], v[228:229] op_sel_hi:[1,0]
	v_pk_mul_f32 v[64:65], v[64:65], v[228:229] op_sel_hi:[1,0]
	v_pk_mul_f32 v[66:67], v[66:67], v[228:229] op_sel_hi:[1,0]
	v_pk_mul_f32 v[52:53], v[52:53], v[228:229] op_sel_hi:[1,0]
	v_pk_mul_f32 v[54:55], v[54:55], v[228:229] op_sel_hi:[1,0]
	v_pk_mul_f32 v[48:49], v[48:49], v[230:231] op_sel_hi:[1,0]
	v_pk_mul_f32 v[50:51], v[50:51], v[230:231] op_sel_hi:[1,0]
	v_pk_mul_f32 v[24:25], v[24:25], v[230:231] op_sel_hi:[1,0]
	v_pk_mul_f32 v[26:27], v[26:27], v[230:231] op_sel_hi:[1,0]
	v_pk_mul_f32 v[28:29], v[28:29], v[230:231] op_sel_hi:[1,0]
	v_pk_mul_f32 v[30:31], v[30:31], v[230:231] op_sel_hi:[1,0]
	v_pk_mul_f32 v[32:33], v[32:33], v[230:231] op_sel_hi:[1,0]
	v_pk_mul_f32 v[34:35], v[34:35], v[230:231] op_sel_hi:[1,0]
	v_pk_mul_f32 v[20:21], v[20:21], v[230:231] op_sel_hi:[1,0]
	v_pk_mul_f32 v[22:23], v[22:23], v[230:231] op_sel_hi:[1,0]
	v_pk_mul_f32 v[16:17], v[16:17], v[232:233] op_sel_hi:[1,0]
	v_pk_mul_f32 v[18:19], v[18:19], v[232:233] op_sel_hi:[1,0]
	v_pk_mul_f32 v[4:5], v[4:5], v[232:233] op_sel_hi:[1,0]
	v_pk_mul_f32 v[6:7], v[6:7], v[232:233] op_sel_hi:[1,0]
	v_pk_mul_f32 v[8:9], v[8:9], v[232:233] op_sel_hi:[1,0]
	v_pk_mul_f32 v[10:11], v[10:11], v[232:233] op_sel_hi:[1,0]
	v_pk_mul_f32 v[12:13], v[12:13], v[232:233] op_sel_hi:[1,0]
	v_pk_mul_f32 v[14:15], v[14:15], v[232:233] op_sel_hi:[1,0]
	v_pk_mul_f32 v[0:1], v[0:1], v[232:233] op_sel_hi:[1,0]
	v_pk_mul_f32 v[2:3], v[2:3], v[232:233] op_sel_hi:[1,0]
.Lmla_rare_a_ns:
	v_cndmask_b32_e64 v221, v221, v216, s[10:11]
	v_cndmask_b32_e64 v222, v222, v217, s[10:11]
	v_cndmask_b32_e64 v223, v223, v218, s[10:11]
	v_cndmask_b32_e64 v224, v224, v219, s[10:11]
	v_add_f32_e32 v241, v241, v221
	v_sub_f32_e32 v180, v180, v221
	v_sub_f32_e32 v181, v181, v221
	v_sub_f32_e32 v182, v182, v221
	v_sub_f32_e32 v183, v183, v221
	v_sub_f32_e32 v196, v196, v221
	v_sub_f32_e32 v197, v197, v221
	v_sub_f32_e32 v198, v198, v221
	v_sub_f32_e32 v199, v199, v221
	v_add_f32_e32 v240, v240, v222
	v_sub_f32_e32 v176, v176, v222
	v_sub_f32_e32 v177, v177, v222
	v_sub_f32_e32 v178, v178, v222
	v_sub_f32_e32 v179, v179, v222
	v_sub_f32_e32 v192, v192, v222
	v_sub_f32_e32 v193, v193, v222
	v_sub_f32_e32 v194, v194, v222
	v_sub_f32_e32 v195, v195, v222
	v_add_f32_e32 v255, v255, v223
	v_sub_f32_e32 v172, v172, v223
	v_sub_f32_e32 v173, v173, v223
	v_sub_f32_e32 v174, v174, v223
	v_sub_f32_e32 v175, v175, v223
	v_sub_f32_e32 v188, v188, v223
	v_sub_f32_e32 v189, v189, v223
	v_sub_f32_e32 v190, v190, v223
	v_sub_f32_e32 v191, v191, v223
	v_add_f32_e32 v40, v40, v224
	v_sub_f32_e32 v168, v168, v224
	v_sub_f32_e32 v169, v169, v224
	v_sub_f32_e32 v170, v170, v224
	v_sub_f32_e32 v171, v171, v224
	v_sub_f32_e32 v184, v184, v224
	v_sub_f32_e32 v185, v185, v224
	v_sub_f32_e32 v186, v186, v224
	v_sub_f32_e32 v187, v187, v224
	v_xor_b32_e32 v160, 0x80000000, v241
	v_xor_b32_e32 v156, 0x80000000, v240
	v_xor_b32_e32 v152, 0x80000000, v255
	v_xor_b32_e32 v164, 0x80000000, v40
	v_mov_b32_e32 v161, v160
	v_mov_b32_e32 v162, v160
	v_mov_b32_e32 v163, v160
	v_mov_b32_e32 v157, v156
	v_mov_b32_e32 v158, v156
	v_mov_b32_e32 v159, v156
	v_mov_b32_e32 v153, v152
	v_mov_b32_e32 v154, v152
	v_mov_b32_e32 v155, v152
	v_mov_b32_e32 v165, v164
	v_mov_b32_e32 v166, v164
	v_mov_b32_e32 v167, v164
	s_mov_b64 s[10:11], 0
	s_branch .Lmla_common_a
; template <int DQK, bool MASK, int NQ>
; __device__ __forceinline__ void attn_unit(unsigned char* lds, const bf16_t* Qg, int ldq, const bf16_t* Kg, int ldk, const bf16_t* Vtg, bf16_t* Og, int ldo,
;                                           int qi0, int a0, int n1, int b0, int n2, float m0, bool sink) {
;     ...
; #pragma unroll
;                 for (int qb = 0; qb < NQ; ++qb) {
;                     float a = fmaxf(fmaxf(sc[0][qb][0], sc[0][qb][1]), sc[0][qb][2]);
;                     a = fmaxf(fmaxf(a, sc[0][qb][3]), sc[1][qb][0]); a = fmaxf(fmaxf(a, sc[1][qb][1]), sc[1][qb][2]); a = fmaxf(a, sc[1][qb][3]);
;                     { auto r16 = __builtin_amdgcn_permlane16_swap(__float_as_uint(a), __float_as_uint(a), false, false); a = fmaxf(__uint_as_float(r16[0]), __uint_as_float(r16[1])); }
;                     { auto r32 = __builtin_amdgcn_permlane32_swap(__float_as_uint(a), __float_as_uint(a), false, false); a = fmaxf(__uint_as_float(r32[0]), __uint_as_float(r32[1])); }
;                     const float dlt = first ? a : fmaxf(a, 0.f);
;                     mrow[qb] += dlt; negm[qb] = (f32x4){-mrow[qb], -mrow[qb], -mrow[qb], -mrow[qb]};
;                     sc[0][qb] = sc[0][qb] - dlt; sc[1][qb] = sc[1][qb] - dlt;
;                     if (!first) { const float alpha = __builtin_amdgcn_exp2f(-dlt); ol[qb] = ol[qb] * alpha;
; #pragma unroll
;                         for (int eb = 0; eb < 4; ++eb) o[eb][qb] = o[eb][qb] * alpha; } }
;                 first = false; }
.Lmla_rare_b:
	s_nop 7
	v_mov_b32_e32 v39, v242
	s_nop 1
	v_permlane16_swap_b32_e32 v242, v39
	v_max_f32_e32 v39, v39, v39
	v_max_f32_e32 v242, v242, v242
	v_max_f32_e32 v242, v242, v39
	v_mov_b32_e32 v39, v242
	s_nop 1
	v_permlane32_swap_b32_e32 v242, v39
	v_max_f32_e32 v39, v39, v39
	v_max_f32_e32 v242, v242, v242
	v_max_f32_e32 v242, v242, v39
	v_max_f32_e32 v180, 0, v242
	v_mov_b32_e32 v39, v243
	s_nop 1
	v_permlane16_swap_b32_e32 v243, v39
	v_max_f32_e32 v39, v39, v39
	v_max_f32_e32 v243, v243, v243
	v_max_f32_e32 v243, v243, v39
	v_mov_b32_e32 v39, v243
	s_nop 1
	v_permlane32_swap_b32_e32 v243, v39
	v_max_f32_e32 v39, v39, v39
	v_max_f32_e32 v243, v243, v243
	v_max_f32_e32 v243, v243, v39
	v_max_f32_e32 v181, 0, v243
	v_mov_b32_e32 v39, v244
	s_nop 1
	v_permlane16_swap_b32_e32 v244, v39
	v_max_f32_e32 v39, v39, v39
	v_max_f32_e32 v244, v244, v244
	v_max_f32_e32 v244, v244, v39
	v_mov_b32_e32 v39, v244
	s_nop 1
	v_permlane32_swap_b32_e32 v244, v39
	v_max_f32_e32 v39, v39, v39
	v_max_f32_e32 v244, v244, v244
	v_max_f32_e32 v244, v244, v39
	v_max_f32_e32 v182, 0, v244
	v_mov_b32_e32 v39, v245
	s_nop 1
	v_permlane16_swap_b32_e32 v245, v39
	v_max_f32_e32 v39, v39, v39
	v_max_f32_e32 v245, v245, v245
	v_max_f32_e32 v245, v245, v39
	v_mov_b32_e32 v39, v245
	s_nop 1
	v_permlane32_swap_b32_e32 v245, v39
	v_max_f32_e32 v39, v39, v39
	v_max_f32_e32 v245, v245, v245
	v_max_f32_e32 v245, v245, v39
	v_max_f32_e32 v183, 0, v245
	s_cmp_lg_u64 s[10:11], 0
	s_cbranch_scc1 .Lmla_rare_b_ns
	v_exp_f32_e64 v184, -v180
	v_exp_f32_e64 v186, -v181
	v_exp_f32_e64 v188, -v182
	v_exp_f32_e64 v190, -v183
	s_nop 0
	v_pk_mul_f32 v[88:89], v[88:89], v[184:185] op_sel_hi:[1,0]
	v_pk_mul_f32 v[90:91], v[90:91], v[184:185] op_sel_hi:[1,0]
	v_pk_mul_f32 v[76:77], v[76:77], v[184:185] op_sel_hi:[1,0]
	v_pk_mul_f32 v[78:79], v[78:79], v[184:185] op_sel_hi:[1,0]
	v_pk_mul_f32 v[80:81], v[80:81], v[184:185] op_sel_hi:[1,0]
	v_pk_mul_f32 v[82:83], v[82:83], v[184:185] op_sel_hi:[1,0]
	v_pk_mul_f32 v[84:85], v[84:85], v[184:185] op_sel_hi:[1,0]
	v_pk_mul_f32 v[86:87], v[86:87], v[184:185] op_sel_hi:[1,0]
	v_pk_mul_f32 v[72:73], v[72:73], v[184:185] op_sel_hi:[1,0]
	v_pk_mul_f32 v[74:75], v[74:75], v[184:185] op_sel_hi:[1,0]
	v_pk_mul_f32 v[68:69], v[68:69], v[186:187] op_sel_hi:[1,0]
	v_pk_mul_f32 v[70:71], v[70:71], v[186:187] op_sel_hi:[1,0]
	v_pk_mul_f32 v[56:57], v[56:57], v[186:187] op_sel_hi:[1,0]
	v_pk_mul_f32 v[58:59], v[58:59], v[186:187] op_sel_hi:[1,0]
	v_pk_mul_f32 v[60:61], v[60:61], v[186:187] op_sel_hi:[1,0]
	v_pk_mul_f32 v[62:63], v[62:63], v[186:187] op_sel_hi:[1,0]
	v_pk_mul_f32 v[64:65], v[64:65], v[186:187] op_sel_hi:[1,0]
	v_pk_mul_f32 v[66:67], v[66:67], v[186:187] op_sel_hi:[1,0]
	v_pk_mul_f32 v[52:53], v[52:53], v[186:187] op_sel_hi:[1,0]
	v_pk_mul_f32 v[54:55], v[54:55], v[186:187] op_sel_hi:[1,0]
	v_pk_mul_f32 v[48:49], v[48:49], v[188:189] op_sel_hi:[1,0]
	v_pk_mul_f32 v[50:51], v[50:51], v[188:189] op_sel_hi:[1,0]
	v_pk_mul_f32 v[24:25], v[24:25], v[188:189] op_sel_hi:[1,0]
	v_pk_mul_f32 v[26:27], v[26:27], v[188:189] op_sel_hi:[1,0]
	v_pk_mul_f32 v[28:29], v[28:29], v[188:189] op_sel_hi:[1,0]
	v_pk_mul_f32 v[30:31], v[30:31], v[188:189] op_sel_hi:[1,0]
	v_pk_mul_f32 v[32:33], v[32:33], v[188:189] op_sel_hi:[1,0]
	v_pk_mul_f32 v[34:35], v[34:35], v[188:189] op_sel_hi:[1,0]
	v_pk_mul_f32 v[20:21], v[20:21], v[188:189] op_sel_hi:[1,0]
	v_pk_mul_f32 v[22:23], v[22:23], v[188:189] op_sel_hi:[1,0]
	v_pk_mul_f32 v[16:17], v[16:17], v[190:191] op_sel_hi:[1,0]
	v_pk_mul_f32 v[18:19], v[18:19], v[190:191] op_sel_hi:[1,0]
	v_pk_mul_f32 v[4:5], v[4:5], v[190:191] op_sel_hi:[1,0]
	v_pk_mul_f32 v[6:7], v[6:7], v[190:191] op_sel_hi:[1,0]
	v_pk_mul_f32 v[8:9], v[8:9], v[190:191] op_sel_hi:[1,0]
	v_pk_mul_f32 v[10:11], v[10:11], v[190:191] op_sel_hi:[1,0]
	v_pk_mul_f32 v[12:13], v[12:13], v[190:191] op_sel_hi:[1,0]
	v_pk_mul_f32 v[14:15], v[14:15], v[190:191] op_sel_hi:[1,0]
	v_pk_mul_f32 v[0:1], v[0:1], v[190:191] op_sel_hi:[1,0]
	v_pk_mul_f32 v[2:3], v[2:3], v[190:191] op_sel_hi:[1,0]
.Lmla_rare_b_ns:
	v_cndmask_b32_e64 v180, v180, v242, s[10:11]
	v_cndmask_b32_e64 v181, v181, v243, s[10:11]
	v_cndmask_b32_e64 v182, v182, v244, s[10:11]
	v_cndmask_b32_e64 v183, v183, v245, s[10:11]
	v_add_f32_e32 v241, v241, v180
	v_sub_f32_e32 v216, v216, v180
	v_sub_f32_e32 v217, v217, v180
	v_sub_f32_e32 v218, v218, v180
	v_sub_f32_e32 v219, v219, v180
	v_sub_f32_e32 v232, v232, v180
	v_sub_f32_e32 v233, v233, v180
	v_sub_f32_e32 v234, v234, v180
	v_sub_f32_e32 v235, v235, v180
	v_add_f32_e32 v240, v240, v181
	v_sub_f32_e32 v220, v220, v181
	v_sub_f32_e32 v221, v221, v181
	v_sub_f32_e32 v222, v222, v181
	v_sub_f32_e32 v223, v223, v181
	v_sub_f32_e32 v44, v44, v181
	v_sub_f32_e32 v45, v45, v181
	v_sub_f32_e32 v46, v46, v181
	v_sub_f32_e32 v47, v47, v181
	v_add_f32_e32 v255, v255, v182
	v_sub_f32_e32 v224, v224, v182
	v_sub_f32_e32 v225, v225, v182
	v_sub_f32_e32 v226, v226, v182
	v_sub_f32_e32 v227, v227, v182
	v_sub_f32_e32 v200, v200, v182
	v_sub_f32_e32 v201, v201, v182
	v_sub_f32_e32 v202, v202, v182
	v_sub_f32_e32 v203, v203, v182
	v_add_f32_e32 v40, v40, v183
	v_sub_f32_e32 v228, v228, v183
	v_sub_f32_e32 v229, v229, v183
	v_sub_f32_e32 v230, v230, v183
	v_sub_f32_e32 v231, v231, v183
	v_sub_f32_e32 v236, v236, v183
	v_sub_f32_e32 v237, v237, v183
	v_sub_f32_e32 v238, v238, v183
	v_sub_f32_e32 v239, v239, v183
	v_xor_b32_e32 v160, 0x80000000, v241
	v_xor_b32_e32 v156, 0x80000000, v240
	v_xor_b32_e32 v152, 0x80000000, v255
	v_xor_b32_e32 v164, 0x80000000, v40
	v_mov_b32_e32 v161, v160
	v_mov_b32_e32 v162, v160
	v_mov_b32_e32 v163, v160
	v_mov_b32_e32 v157, v156
	v_mov_b32_e32 v158, v156
	v_mov_b32_e32 v159, v156
	v_mov_b32_e32 v153, v152
	v_mov_b32_e32 v154, v152
	v_mov_b32_e32 v155, v152
	v_mov_b32_e32 v165, v164
	v_mov_b32_e32 v166, v164
	v_mov_b32_e32 v167, v164
	s_mov_b64 s[10:11], 0
	s_branch .Lmla_common_b
.Lmla_exit:
	v_add_u32_e32 v37, 0xd000, v205
	ds_read_b128 v[44:47], v37
	ds_read_b128 v[200:203], v37 offset:8192
	ds_read_b128 v[216:219], v37 offset:16384
	ds_read_b128 v[220:223], v37 offset:24576
	ds_read_b128 v[224:227], v37 offset:32768
	ds_read_b128 v[228:231], v37 offset:40960
	ds_read_b128 v[232:235], v37 offset:49152
	ds_read_b32 v40, v37 offset:57344
	ds_read_b64 v[250:251], v37 offset:57352
	s_waitcnt lgkmcnt(0)
	s_branch .LBB0_405

; __global__ void __launch_bounds__(NTHR, 2) mk_fwd(Args args) {
	.amdhsa_kernel _Z6mk_fwd4Args
		.amdhsa_group_segment_fixed_size 0
		.amdhsa_private_segment_fixed_size 0
		.amdhsa_kernarg_size 488
		.amdhsa_user_sgpr_count 2
		.amdhsa_user_sgpr_dispatch_ptr 0
		.amdhsa_user_sgpr_queue_ptr 0
		.amdhsa_user_sgpr_kernarg_segment_ptr 1
		.amdhsa_user_sgpr_dispatch_id 0
		.amdhsa_user_sgpr_kernarg_preload_length 0
		.amdhsa_user_sgpr_kernarg_preload_offset 0
		.amdhsa_user_sgpr_private_segment_size 0
		.amdhsa_uses_dynamic_stack 0
		.amdhsa_enable_private_segment 0
		.amdhsa_system_sgpr_workgroup_id_x 1
		.amdhsa_system_sgpr_workgroup_id_y 0
		.amdhsa_system_sgpr_workgroup_id_z 0
		.amdhsa_system_sgpr_workgroup_info 0
		.amdhsa_system_vgpr_workitem_id 2
		.amdhsa_next_free_vgpr 256
		.amdhsa_next_free_sgpr 100
		.amdhsa_accum_offset 256
		.amdhsa_reserve_vcc 1
		.amdhsa_float_round_mode_32 0
		.amdhsa_float_round_mode_16_64 0
		.amdhsa_float_denorm_mode_32 3
		.amdhsa_float_denorm_mode_16_64 3
		.amdhsa_dx10_clamp 1
		.amdhsa_ieee_mode 1
		.amdhsa_fp16_overflow 0
		.amdhsa_tg_split 0
		.amdhsa_exception_fp_ieee_invalid_op 0
		.amdhsa_exception_fp_denorm_src 0
		.amdhsa_exception_fp_ieee_div_zero 0
		.amdhsa_exception_fp_ieee_overflow 0
		.amdhsa_exception_fp_ieee_underflow 0
		.amdhsa_exception_fp_ieee_inexact 0
		.amdhsa_exception_int_div_zero 0
	.end_amdhsa_kernel

; __global__ void __launch_bounds__(NTHR, 2) mk_fwd(Args args) {
amdhsa.kernels:
  - .agpr_count:     0
    .args:
      - .offset:         0
        .size:           232
        .value_kind:     by_value
      - .offset:         232
        .size:           4
        .value_kind:     hidden_block_count_x
      - .offset:         236
        .size:           4
        .value_kind:     hidden_block_count_y
      - .offset:         240
        .size:           4
        .value_kind:     hidden_block_count_z
      - .offset:         244
        .size:           2
        .value_kind:     hidden_group_size_x
      - .offset:         246
        .size:           2
        .value_kind:     hidden_group_size_y
      - .offset:         248
        .size:           2
        .value_kind:     hidden_group_size_z
      - .offset:         250
        .size:           2
        .value_kind:     hidden_remainder_x
      - .offset:         252
        .size:           2
        .value_kind:     hidden_remainder_y
      - .offset:         254
        .size:           2
        .value_kind:     hidden_remainder_z
      - .offset:         272
        .size:           8
        .value_kind:     hidden_global_offset_x
      - .offset:         280
        .size:           8
        .value_kind:     hidden_global_offset_y
      - .offset:         288
        .size:           8
        .value_kind:     hidden_global_offset_z
      - .offset:         296
        .size:           2
        .value_kind:     hidden_grid_dims
      - .offset:         320
        .size:           8
        .value_kind:     hidden_multigrid_sync_arg
      - .offset:         352
        .size:           4
        .value_kind:     hidden_dynamic_lds_size
    .group_segment_fixed_size: 0
    .kernarg_segment_align: 8
    .kernarg_segment_size: 488
    .language:       OpenCL C
    .language_version:
      - 2
      - 0
    .max_flat_workgroup_size: 512
    .name:           _Z6mk_fwd4Args
    .private_segment_fixed_size: 0
    .sgpr_count:     106
    .sgpr_spill_count: 191
    .symbol:         _Z6mk_fwd4Args.kd
    .uniform_work_group_size: 1
    .uses_dynamic_stack: false
    .vgpr_count:     256
    .vgpr_spill_count: 0
    .wavefront_size: 64
